# speedup vs baseline: 1.0609x; 1.0098x over previous
; __device__ __forceinline__ void attn_item(const int WV, const Params& P, int bh, int qb) {
;     ...
;   auto compute = [&](const int kt, const char* cur) {
;     if (kt * 64 <= q0 + 31) {
;       const float* cks = (const float*)(cur + 128 * KP);
;       f32x16 st[2];
; #pragma unroll
;       for (int kb = 0; kb < 2; ++kb) {
; #pragma unroll
;         for (int gq = 0; gq < 4; ++gq) {
;           f32x4 ck4 = *(const f32x4*)(cks + kb * 32 + gq * 8 + hf * 4);
;           st[kb][gq * 4 + 0] = ck4[0]; st[kb][gq * 4 + 1] = ck4[1]; st[kb][gq * 4 + 2] = ck4[2]; st[kb][gq * 4 + 3] = ck4[3];
;         }
; #pragma unroll
;         for (int s = 0; s < 4; ++s) {
;           bf16x8 a = *(const bf16x8*)(cur + (kb * 32 + n) * KP + s * 32 + hf * 16);
;           st[kb] = __builtin_amdgcn_mfma_f32_32x32x16_bf16(a, qf[s], st[kb], 0, 0, 0);
;         }
;       }
;       if (kt * 64 + 63 > q0) {
; #pragma unroll
;         for (int kb = 0; kb < 2; ++kb)
; #pragma unroll
;           for (int i = 0; i < 16; ++i) {
;             int key = kt * 64 + kb * 32 + (i >> 2) * 8 + hf * 4 + (i & 3);
;             if (key > q0 + n) st[kb][i] = -INFINITY;
;           }
;       }
;       float mx = -INFINITY;
; #pragma unroll
;       for (int kb = 0; kb < 2; ++kb)
; #pragma unroll
;         for (int i = 0; i < 16; ++i) mx = fmaxf(mx, st[kb][i]);
;       {
;         auto rr = __builtin_amdgcn_permlane32_swap(__float_as_uint(mx), __float_as_uint(mx), false, false);
;         mx = fmaxf(__uint_as_float(rr[0]), __uint_as_float(rr[1]));
;       }
;       const float mn = fmaxf(m, mx);
;       const float alpha = __builtin_amdgcn_exp2f(m - mn);
;     ...
;   for (int kt = 0; kt < nkt; kt += 2) {
;     compute(kt, sm + (kt & 3) * BUFSZ);
;     compute(kt + 1, sm + ((kt + 1) & 3) * BUFSZ);
.LBB0_386:
	s_add_i32 s33, s29, -3
	v_readfirstlane_b32 s20, v162
	s_nop 3
	s_cmp_lt_u32 s20, 0x100
	s_cbranch_scc1 .Lat2_slow
	s_add_i32 s20, s28, 0x7f
	v_cmp_le_i32_e32 vcc, s20, v116
	s_cmp_eq_u64 vcc, exec
	s_cbranch_scc0 .Lat2_slow
	s_mov_b64 s[12:13], exec
	s_and_b32 s34, s33, 2
	s_mulk_i32 s34, 0x4900
	v_add3_u32 v241, s34, v134, v128
	v_lshrrev_b32_e32 v242, 2, v162
	v_and_b32_e32 v242, 8, v242
	v_add_u32_e32 v241, v241, v242
	v_add_u32_e32 v175, 0x2000, v241
	v_add_u32_e32 v174, 0x3000, v241
	v_lshl_or_b32 v0, v113, 2, s34
	v_or_b32_e32 v2, s34, v118
	ds_read_b128 v[64:67], v0 offset:18432
	ds_read_b128 v[68:71], v0 offset:18464
	ds_read_b128 v[72:75], v0 offset:18496
	ds_read_b128 v[76:79], v0 offset:18528
	v_add_u32_e32 v10, v2, v134
	ds_read_b128 v[208:211], v10
	ds_read_b128 v[212:215], v10 offset:32
	ds_read_b128 v[216:219], v10 offset:64
	ds_read_b128 v[220:223], v10 offset:96
	ds_read_b128 v[48:51], v0 offset:18560
	ds_read_b128 v[52:55], v0 offset:18592
	ds_read_b128 v[56:59], v0 offset:18624
	ds_read_b128 v[60:63], v0 offset:18656
	ds_read_b128 v[224:227], v10 offset:4608
	ds_read_b128 v[228:231], v10 offset:4640
	ds_read_b128 v[232:235], v10 offset:4672
	s_waitcnt lgkmcnt(10)
	v_mfma_f32_32x32x16_bf16 v[64:79], v[208:211], v[80:83], v[64:79]
	ds_read_b128 v[236:239], v10 offset:4704
	s_waitcnt lgkmcnt(10)
	v_mfma_f32_32x32x16_bf16 v[64:79], v[212:215], v[84:87], v[64:79]
	s_waitcnt lgkmcnt(9)
	v_mfma_f32_32x32x16_bf16 v[64:79], v[216:219], v[88:91], v[64:79]
	s_waitcnt lgkmcnt(8)
	v_mfma_f32_32x32x16_bf16 v[64:79], v[220:223], v[92:95], v[64:79]
	s_waitcnt lgkmcnt(3)
	v_mfma_f32_32x32x16_bf16 v[48:63], v[224:227], v[80:83], v[48:63]
	s_waitcnt lgkmcnt(2)
	v_mfma_f32_32x32x16_bf16 v[48:63], v[228:231], v[84:87], v[48:63]
	s_waitcnt lgkmcnt(1)
	v_mfma_f32_32x32x16_bf16 v[48:63], v[232:235], v[88:91], v[48:63]
	s_waitcnt lgkmcnt(0)
	v_mfma_f32_32x32x16_bf16 v[48:63], v[236:239], v[92:95], v[48:63]
	s_add_i32 s20, s29, -2
	s_and_b32 s34, s20, 3
	s_mulk_i32 s34, 0x4900
	v_lshl_or_b32 v0, v113, 2, s34
	v_or_b32_e32 v2, s34, v118
	ds_read_b128 v[176:179], v0 offset:18432
	ds_read_b128 v[180:183], v0 offset:18464
	ds_read_b128 v[184:187], v0 offset:18496
	ds_read_b128 v[188:191], v0 offset:18528
	v_add_u32_e32 v10, v2, v134
	ds_read_b128 v[208:211], v10
	ds_read_b128 v[212:215], v10 offset:32
	ds_read_b128 v[216:219], v10 offset:64
	ds_read_b128 v[220:223], v10 offset:96
	ds_read_b128 v[192:195], v0 offset:18560
	ds_read_b128 v[196:199], v0 offset:18592
	ds_read_b128 v[200:203], v0 offset:18624
	ds_read_b128 v[204:207], v0 offset:18656
	ds_read_b128 v[224:227], v10 offset:4608
	ds_read_b128 v[228:231], v10 offset:4640
	ds_read_b128 v[232:235], v10 offset:4672
	s_waitcnt lgkmcnt(10)
	v_mfma_f32_32x32x16_bf16 v[176:191], v[208:211], v[80:83], v[176:191]
	ds_read_b128 v[236:239], v10 offset:4704
	s_waitcnt lgkmcnt(10)
	v_mfma_f32_32x32x16_bf16 v[176:191], v[212:215], v[84:87], v[176:191]
	s_waitcnt lgkmcnt(9)
	v_mfma_f32_32x32x16_bf16 v[176:191], v[216:219], v[88:91], v[176:191]
	s_waitcnt lgkmcnt(8)
	v_mfma_f32_32x32x16_bf16 v[176:191], v[220:223], v[92:95], v[176:191]
	s_waitcnt lgkmcnt(3)
	v_mfma_f32_32x32x16_bf16 v[192:207], v[224:227], v[80:83], v[192:207]
	s_waitcnt lgkmcnt(2)
	v_mfma_f32_32x32x16_bf16 v[192:207], v[228:231], v[84:87], v[192:207]
	s_waitcnt lgkmcnt(1)
	v_mfma_f32_32x32x16_bf16 v[192:207], v[232:235], v[88:91], v[192:207]
	s_waitcnt lgkmcnt(0)
	v_mfma_f32_32x32x16_bf16 v[192:207], v[236:239], v[92:95], v[192:207]
	ds_read_b128 v[208:211], v175 offset:1024
	ds_read_b128 v[212:215], v174 offset:1536
	ds_read_b128 v[216:219], v175 offset:1056
	ds_read_b128 v[220:223], v174 offset:1568
	ds_read_b128 v[224:227], v175 offset:1088
	ds_read_b128 v[228:231], v174 offset:1600
	ds_read_b128 v[232:235], v175 offset:1120
	ds_read_b128 v[236:239], v174 offset:1632
	v_max3_f32 v0, v64, s76, v65
	v_max3_f32 v2, v48, s76, v49
	v_max3_f32 v0, v0, v66, v67
	v_max3_f32 v2, v2, v50, v51
	v_max3_f32 v0, v0, v68, v69
	v_max3_f32 v2, v2, v52, v53
	v_max3_f32 v0, v0, v70, v71
	v_max3_f32 v2, v2, v54, v55
	v_max3_f32 v0, v0, v72, v73
	v_max3_f32 v2, v2, v56, v57
	v_max3_f32 v0, v0, v74, v75
	v_max3_f32 v2, v2, v58, v59
	v_max3_f32 v0, v0, v76, v77
	v_max3_f32 v2, v2, v60, v61
	v_max3_f32 v0, v0, v78, v79
	v_max3_f32 v2, v2, v62, v63
	v_max_f32_e32 v0, v0, v2
	v_mov_b32_e32 v2, v0
	s_nop 1
	v_permlane32_swap_b32_e32 v0, v2
	v_max_f32_e32 v0, v0, v2
	v_sub_f32_e32 v2, v0, v137
	v_cmp_lt_f32_e32 vcc, 0x41c00000, v2
	s_cbranch_vccz .Lat2_noresc_a
	v_max_f32_e32 v138, v137, v0
	v_sub_f32_e32 v2, v137, v138
	v_exp_f32_e32 v2, v2
	v_mov_b32_e32 v137, v138
	s_nop 0
	v_mul_f32_e32 v136, v136, v2
	v_mul_f32_e32 v32, v32, v2
	v_mul_f32_e32 v33, v33, v2
	v_mul_f32_e32 v34, v34, v2
	v_mul_f32_e32 v35, v35, v2
	v_mul_f32_e32 v36, v36, v2
	v_mul_f32_e32 v37, v37, v2
	v_mul_f32_e32 v38, v38, v2
	v_mul_f32_e32 v39, v39, v2
	v_mul_f32_e32 v40, v40, v2
	v_mul_f32_e32 v41, v41, v2
	v_mul_f32_e32 v42, v42, v2
	v_mul_f32_e32 v43, v43, v2
	v_mul_f32_e32 v44, v44, v2
	v_mul_f32_e32 v45, v45, v2
	v_mul_f32_e32 v46, v46, v2
	v_mul_f32_e32 v47, v47, v2
	v_mul_f32_e32 v16, v16, v2
	v_mul_f32_e32 v17, v17, v2
	v_mul_f32_e32 v18, v18, v2
	v_mul_f32_e32 v19, v19, v2
	v_mul_f32_e32 v20, v20, v2
	v_mul_f32_e32 v21, v21, v2
	v_mul_f32_e32 v22, v22, v2
	v_mul_f32_e32 v23, v23, v2
	v_mul_f32_e32 v24, v24, v2
	v_mul_f32_e32 v25, v25, v2
	v_mul_f32_e32 v26, v26, v2
	v_mul_f32_e32 v27, v27, v2
	v_mul_f32_e32 v28, v28, v2
	v_mul_f32_e32 v29, v29, v2
	v_mul_f32_e32 v30, v30, v2
	v_mul_f32_e32 v31, v31, v2
; __device__ __forceinline__ void attn_item(const int WV, const Params& P, int bh, int qb) {
;     ...
;       const float mn = fmaxf(m, mx);
;       const float alpha = __builtin_amdgcn_exp2f(m - mn);
;       m = mn;
;       float ps = 0.f;
;       bf16x8 pb[4];
; #pragma unroll
;       for (int kb = 0; kb < 2; ++kb)
; #pragma unroll
;         for (int i = 0; i < 16; i += 2) {
;           float p0 = __builtin_amdgcn_exp2f(st[kb][i] - mn), p1 = __builtin_amdgcn_exp2f(st[kb][i + 1] - mn);
;           ps += p0 + p1;
;           unsigned pk = pack2bf(p0, p1);
;           pb[kb * 2 + (i >> 3)][i & 7] = (short)(pk & 0xffff);
;           pb[kb * 2 + (i >> 3)][(i & 7) + 1] = (short)(pk >> 16);
;         }
;       l = l * alpha + ps;
; #pragma unroll
;       for (int i = 0; i < 16; ++i) { ot[0][i] *= alpha; ot[1][i] *= alpha; }
;       const char* vb = cur + 64 * KP;
; #pragma unroll
;       for (int db = 0; db < 2; ++db)
; #pragma unroll
;         for (int s = 0; s < 4; ++s) {
;           const char* rp = vb + (db * 32 + n) * KP + (16 * s + 4 * hf) * 2;
;           typedef __attribute__((ext_vector_type(4))) short s16x4;
;           s16x4 lo = *(const s16x4*)rp, hi = *(const s16x4*)(rp + 16);
;           bf16x8 a;
;           a[0] = lo[0]; a[1] = lo[1]; a[2] = lo[2]; a[3] = lo[3]; a[4] = hi[0]; a[5] = hi[1]; a[6] = hi[2]; a[7] = hi[3];
;           ot[db] = __builtin_amdgcn_mfma_f32_32x32x16_bf16(a, pb[s], ot[db], 0, 0, 0);
;         }
;     }
.Lat2_noresc_a:
	v_sub_f32_e32 v64, v64, v137
	v_sub_f32_e32 v65, v65, v137
	v_sub_f32_e32 v66, v66, v137
	v_sub_f32_e32 v67, v67, v137
	v_sub_f32_e32 v68, v68, v137
	v_sub_f32_e32 v69, v69, v137
	v_sub_f32_e32 v70, v70, v137
	v_sub_f32_e32 v71, v71, v137
	v_exp_f32_e32 v64, v64
	v_exp_f32_e32 v65, v65
	v_exp_f32_e32 v66, v66
	v_exp_f32_e32 v67, v67
	v_exp_f32_e32 v68, v68
	v_exp_f32_e32 v69, v69
	v_exp_f32_e32 v70, v70
	v_exp_f32_e32 v71, v71
	v_cvt_pk_bf16_f32 v2, v64, v65
	v_cvt_pk_bf16_f32 v3, v66, v67
	v_cvt_pk_bf16_f32 v4, v68, v69
	v_cvt_pk_bf16_f32 v5, v70, v71
	v_add_f32_e32 v14, v64, v65
	v_add_f32_e32 v15, v66, v67
	v_add_f32_e32 v0, v68, v69
	v_add_f32_e32 v245, v70, v71
	v_add_f32_e32 v14, v14, v15
	v_add_f32_e32 v0, v0, v245
	v_add_f32_e32 v14, v14, v0
	v_mov_b32_e32 v244, v14
	s_waitcnt lgkmcnt(6)
	v_mfma_f32_32x32x16_bf16 v[32:47], v[208:211], v[2:5], v[32:47]
	v_mfma_f32_32x32x16_bf16 v[16:31], v[212:215], v[2:5], v[16:31]
	v_sub_f32_e32 v72, v72, v137
	v_sub_f32_e32 v73, v73, v137
	v_sub_f32_e32 v74, v74, v137
	v_sub_f32_e32 v75, v75, v137
	v_sub_f32_e32 v76, v76, v137
	v_sub_f32_e32 v77, v77, v137
	v_sub_f32_e32 v78, v78, v137
	v_sub_f32_e32 v79, v79, v137
	v_exp_f32_e32 v72, v72
	v_exp_f32_e32 v73, v73
	v_exp_f32_e32 v74, v74
	v_exp_f32_e32 v75, v75
	v_exp_f32_e32 v76, v76
	v_exp_f32_e32 v77, v77
	v_exp_f32_e32 v78, v78
	v_exp_f32_e32 v79, v79
	v_cvt_pk_bf16_f32 v6, v72, v73
	v_cvt_pk_bf16_f32 v7, v74, v75
	v_cvt_pk_bf16_f32 v8, v76, v77
	v_cvt_pk_bf16_f32 v9, v78, v79
	v_add_f32_e32 v14, v72, v73
	v_add_f32_e32 v15, v74, v75
	v_add_f32_e32 v0, v76, v77
	v_add_f32_e32 v245, v78, v79
	v_add_f32_e32 v14, v14, v15
	v_add_f32_e32 v0, v0, v245
	v_add_f32_e32 v14, v14, v0
	v_add_f32_e32 v244, v244, v14
	s_waitcnt lgkmcnt(4)
	v_mfma_f32_32x32x16_bf16 v[32:47], v[216:219], v[6:9], v[32:47]
	v_mfma_f32_32x32x16_bf16 v[16:31], v[220:223], v[6:9], v[16:31]
	v_sub_f32_e32 v48, v48, v137
	v_sub_f32_e32 v49, v49, v137
	v_sub_f32_e32 v50, v50, v137
	v_sub_f32_e32 v51, v51, v137
	v_sub_f32_e32 v52, v52, v137
	v_sub_f32_e32 v53, v53, v137
	v_sub_f32_e32 v54, v54, v137
	v_sub_f32_e32 v55, v55, v137
	v_exp_f32_e32 v48, v48
	v_exp_f32_e32 v49, v49
	v_exp_f32_e32 v50, v50
	v_exp_f32_e32 v51, v51
	v_exp_f32_e32 v52, v52
	v_exp_f32_e32 v53, v53
	v_exp_f32_e32 v54, v54
	v_exp_f32_e32 v55, v55
	v_cvt_pk_bf16_f32 v10, v48, v49
	v_cvt_pk_bf16_f32 v11, v50, v51
	v_cvt_pk_bf16_f32 v12, v52, v53
	v_cvt_pk_bf16_f32 v13, v54, v55
	v_add_f32_e32 v14, v48, v49
	v_add_f32_e32 v15, v50, v51
	v_add_f32_e32 v0, v52, v53
	v_add_f32_e32 v245, v54, v55
	v_add_f32_e32 v14, v14, v15
	v_add_f32_e32 v0, v0, v245
	v_add_f32_e32 v14, v14, v0
	v_add_f32_e32 v244, v244, v14
	s_waitcnt lgkmcnt(2)
	v_mfma_f32_32x32x16_bf16 v[32:47], v[224:227], v[10:13], v[32:47]
	v_mfma_f32_32x32x16_bf16 v[16:31], v[228:231], v[10:13], v[16:31]
	v_sub_f32_e32 v56, v56, v137
	v_sub_f32_e32 v57, v57, v137
	v_sub_f32_e32 v58, v58, v137
	v_sub_f32_e32 v59, v59, v137
	v_sub_f32_e32 v60, v60, v137
	v_sub_f32_e32 v61, v61, v137
	v_sub_f32_e32 v62, v62, v137
	v_sub_f32_e32 v63, v63, v137
	v_exp_f32_e32 v56, v56
	v_exp_f32_e32 v57, v57
	v_exp_f32_e32 v58, v58
	v_exp_f32_e32 v59, v59
	v_exp_f32_e32 v60, v60
	v_exp_f32_e32 v61, v61
	v_exp_f32_e32 v62, v62
	v_exp_f32_e32 v63, v63
	v_cvt_pk_bf16_f32 v246, v56, v57
	v_cvt_pk_bf16_f32 v247, v58, v59
	v_cvt_pk_bf16_f32 v248, v60, v61
	v_cvt_pk_bf16_f32 v249, v62, v63
	v_add_f32_e32 v14, v56, v57
	v_add_f32_e32 v15, v58, v59
	v_add_f32_e32 v0, v60, v61
	v_add_f32_e32 v245, v62, v63
	v_add_f32_e32 v14, v14, v15
	v_add_f32_e32 v0, v0, v245
	v_add_f32_e32 v14, v14, v0
	v_add_f32_e32 v244, v244, v14
	s_waitcnt lgkmcnt(0)
	v_mfma_f32_32x32x16_bf16 v[32:47], v[232:235], v[246:249], v[32:47]
	v_mfma_f32_32x32x16_bf16 v[16:31], v[236:239], v[246:249], v[16:31]
	v_add_f32_e32 v136, v136, v244
	v_add3_u32 v241, s34, v134, v128
	v_lshrrev_b32_e32 v242, 2, v162
	v_and_b32_e32 v242, 8, v242
	v_add_u32_e32 v241, v241, v242
	v_add_u32_e32 v242, 0x2000, v241
	v_add_u32_e32 v243, 0x3000, v241
	ds_read_b128 v[208:211], v242 offset:1024
	ds_read_b128 v[212:215], v243 offset:1536
	ds_read_b128 v[216:219], v242 offset:1056
	ds_read_b128 v[220:223], v243 offset:1568
	ds_read_b128 v[224:227], v242 offset:1088
	ds_read_b128 v[228:231], v243 offset:1600
	ds_read_b128 v[232:235], v242 offset:1120
	ds_read_b128 v[236:239], v243 offset:1632
	v_max3_f32 v0, v176, s76, v177
	v_max3_f32 v2, v192, s76, v193
	v_max3_f32 v0, v0, v178, v179
	v_max3_f32 v2, v2, v194, v195
	v_max3_f32 v0, v0, v180, v181
	v_max3_f32 v2, v2, v196, v197
	v_max3_f32 v0, v0, v182, v183
	v_max3_f32 v2, v2, v198, v199
	v_max3_f32 v0, v0, v184, v185
	v_max3_f32 v2, v2, v200, v201
	v_max3_f32 v0, v0, v186, v187
	v_max3_f32 v2, v2, v202, v203
	v_max3_f32 v0, v0, v188, v189
	v_max3_f32 v2, v2, v204, v205
	v_max3_f32 v0, v0, v190, v191
	v_max3_f32 v2, v2, v206, v207
	v_max_f32_e32 v0, v0, v2
	v_mov_b32_e32 v2, v0
	s_nop 1
	v_permlane32_swap_b32_e32 v0, v2
	v_max_f32_e32 v0, v0, v2
	v_sub_f32_e32 v2, v0, v137
	v_cmp_lt_f32_e32 vcc, 0x41c00000, v2
	s_cbranch_vccz .Lat2_noresc_b
	v_max_f32_e32 v138, v137, v0
	v_sub_f32_e32 v2, v137, v138
	v_exp_f32_e32 v2, v2
	v_mov_b32_e32 v137, v138
	s_nop 0
	v_mul_f32_e32 v136, v136, v2
	v_mul_f32_e32 v32, v32, v2
	v_mul_f32_e32 v33, v33, v2
	v_mul_f32_e32 v34, v34, v2
	v_mul_f32_e32 v35, v35, v2
	v_mul_f32_e32 v36, v36, v2
	v_mul_f32_e32 v37, v37, v2
	v_mul_f32_e32 v38, v38, v2
	v_mul_f32_e32 v39, v39, v2
	v_mul_f32_e32 v40, v40, v2
	v_mul_f32_e32 v41, v41, v2
	v_mul_f32_e32 v42, v42, v2
	v_mul_f32_e32 v43, v43, v2
	v_mul_f32_e32 v44, v44, v2
	v_mul_f32_e32 v45, v45, v2
	v_mul_f32_e32 v46, v46, v2
	v_mul_f32_e32 v47, v47, v2
	v_mul_f32_e32 v16, v16, v2
	v_mul_f32_e32 v17, v17, v2
	v_mul_f32_e32 v18, v18, v2
	v_mul_f32_e32 v19, v19, v2
	v_mul_f32_e32 v20, v20, v2
	v_mul_f32_e32 v21, v21, v2
	v_mul_f32_e32 v22, v22, v2
	v_mul_f32_e32 v23, v23, v2
	v_mul_f32_e32 v24, v24, v2
	v_mul_f32_e32 v25, v25, v2
	v_mul_f32_e32 v26, v26, v2
	v_mul_f32_e32 v27, v27, v2
	v_mul_f32_e32 v28, v28, v2
	v_mul_f32_e32 v29, v29, v2
	v_mul_f32_e32 v30, v30, v2
	v_mul_f32_e32 v31, v31, v2
; __device__ __forceinline__ void attn_item(const int WV, const Params& P, int bh, int qb) {
;     ...
;       const float mn = fmaxf(m, mx);
;       const float alpha = __builtin_amdgcn_exp2f(m - mn);
;       m = mn;
;       float ps = 0.f;
;       bf16x8 pb[4];
; #pragma unroll
;       for (int kb = 0; kb < 2; ++kb)
; #pragma unroll
;         for (int i = 0; i < 16; i += 2) {
;           float p0 = __builtin_amdgcn_exp2f(st[kb][i] - mn), p1 = __builtin_amdgcn_exp2f(st[kb][i + 1] - mn);
;           ps += p0 + p1;
;           unsigned pk = pack2bf(p0, p1);
;           pb[kb * 2 + (i >> 3)][i & 7] = (short)(pk & 0xffff);
;           pb[kb * 2 + (i >> 3)][(i & 7) + 1] = (short)(pk >> 16);
;         }
;       l = l * alpha + ps;
; #pragma unroll
;       for (int i = 0; i < 16; ++i) { ot[0][i] *= alpha; ot[1][i] *= alpha; }
;       const char* vb = cur + 64 * KP;
; #pragma unroll
;       for (int db = 0; db < 2; ++db)
; #pragma unroll
;         for (int s = 0; s < 4; ++s) {
;           const char* rp = vb + (db * 32 + n) * KP + (16 * s + 4 * hf) * 2;
;           typedef __attribute__((ext_vector_type(4))) short s16x4;
;           s16x4 lo = *(const s16x4*)rp, hi = *(const s16x4*)(rp + 16);
;           bf16x8 a;
;           a[0] = lo[0]; a[1] = lo[1]; a[2] = lo[2]; a[3] = lo[3]; a[4] = hi[0]; a[5] = hi[1]; a[6] = hi[2]; a[7] = hi[3];
;           ot[db] = __builtin_amdgcn_mfma_f32_32x32x16_bf16(a, pb[s], ot[db], 0, 0, 0);
;         }
;     }
.Lat2_noresc_b:
	v_sub_f32_e32 v176, v176, v137
	v_sub_f32_e32 v177, v177, v137
	v_sub_f32_e32 v178, v178, v137
	v_sub_f32_e32 v179, v179, v137
	v_sub_f32_e32 v180, v180, v137
	v_sub_f32_e32 v181, v181, v137
	v_sub_f32_e32 v182, v182, v137
	v_sub_f32_e32 v183, v183, v137
	v_exp_f32_e32 v176, v176
	v_exp_f32_e32 v177, v177
	v_exp_f32_e32 v178, v178
	v_exp_f32_e32 v179, v179
	v_exp_f32_e32 v180, v180
	v_exp_f32_e32 v181, v181
	v_exp_f32_e32 v182, v182
	v_exp_f32_e32 v183, v183
	v_cvt_pk_bf16_f32 v2, v176, v177
	v_cvt_pk_bf16_f32 v3, v178, v179
	v_cvt_pk_bf16_f32 v4, v180, v181
	v_cvt_pk_bf16_f32 v5, v182, v183
	v_add_f32_e32 v14, v176, v177
	v_add_f32_e32 v15, v178, v179
	v_add_f32_e32 v0, v180, v181
	v_add_f32_e32 v245, v182, v183
	v_add_f32_e32 v14, v14, v15
	v_add_f32_e32 v0, v0, v245
	v_add_f32_e32 v14, v14, v0
	v_mov_b32_e32 v244, v14
	s_waitcnt lgkmcnt(6)
	v_mfma_f32_32x32x16_bf16 v[32:47], v[208:211], v[2:5], v[32:47]
	v_mfma_f32_32x32x16_bf16 v[16:31], v[212:215], v[2:5], v[16:31]
	v_sub_f32_e32 v184, v184, v137
	v_sub_f32_e32 v185, v185, v137
	v_sub_f32_e32 v186, v186, v137
	v_sub_f32_e32 v187, v187, v137
	v_sub_f32_e32 v188, v188, v137
	v_sub_f32_e32 v189, v189, v137
	v_sub_f32_e32 v190, v190, v137
	v_sub_f32_e32 v191, v191, v137
	v_exp_f32_e32 v184, v184
	v_exp_f32_e32 v185, v185
	v_exp_f32_e32 v186, v186
	v_exp_f32_e32 v187, v187
	v_exp_f32_e32 v188, v188
	v_exp_f32_e32 v189, v189
	v_exp_f32_e32 v190, v190
	v_exp_f32_e32 v191, v191
	v_cvt_pk_bf16_f32 v6, v184, v185
	v_cvt_pk_bf16_f32 v7, v186, v187
	v_cvt_pk_bf16_f32 v8, v188, v189
	v_cvt_pk_bf16_f32 v9, v190, v191
	v_add_f32_e32 v14, v184, v185
	v_add_f32_e32 v15, v186, v187
	v_add_f32_e32 v0, v188, v189
	v_add_f32_e32 v245, v190, v191
	v_add_f32_e32 v14, v14, v15
	v_add_f32_e32 v0, v0, v245
	v_add_f32_e32 v14, v14, v0
	v_add_f32_e32 v244, v244, v14
	s_waitcnt lgkmcnt(4)
	v_mfma_f32_32x32x16_bf16 v[32:47], v[216:219], v[6:9], v[32:47]
	v_mfma_f32_32x32x16_bf16 v[16:31], v[220:223], v[6:9], v[16:31]
	v_sub_f32_e32 v192, v192, v137
	v_sub_f32_e32 v193, v193, v137
	v_sub_f32_e32 v194, v194, v137
	v_sub_f32_e32 v195, v195, v137
	v_sub_f32_e32 v196, v196, v137
	v_sub_f32_e32 v197, v197, v137
	v_sub_f32_e32 v198, v198, v137
	v_sub_f32_e32 v199, v199, v137
	v_exp_f32_e32 v192, v192
	v_exp_f32_e32 v193, v193
	v_exp_f32_e32 v194, v194
	v_exp_f32_e32 v195, v195
	v_exp_f32_e32 v196, v196
	v_exp_f32_e32 v197, v197
	v_exp_f32_e32 v198, v198
	v_exp_f32_e32 v199, v199
	v_cvt_pk_bf16_f32 v10, v192, v193
	v_cvt_pk_bf16_f32 v11, v194, v195
	v_cvt_pk_bf16_f32 v12, v196, v197
	v_cvt_pk_bf16_f32 v13, v198, v199
	v_add_f32_e32 v14, v192, v193
	v_add_f32_e32 v15, v194, v195
	v_add_f32_e32 v0, v196, v197
	v_add_f32_e32 v245, v198, v199
	v_add_f32_e32 v14, v14, v15
	v_add_f32_e32 v0, v0, v245
	v_add_f32_e32 v14, v14, v0
	v_add_f32_e32 v244, v244, v14
	s_waitcnt lgkmcnt(2)
	v_mfma_f32_32x32x16_bf16 v[32:47], v[224:227], v[10:13], v[32:47]
	v_mfma_f32_32x32x16_bf16 v[16:31], v[228:231], v[10:13], v[16:31]
	v_sub_f32_e32 v200, v200, v137
	v_sub_f32_e32 v201, v201, v137
	v_sub_f32_e32 v202, v202, v137
	v_sub_f32_e32 v203, v203, v137
	v_sub_f32_e32 v204, v204, v137
	v_sub_f32_e32 v205, v205, v137
	v_sub_f32_e32 v206, v206, v137
	v_sub_f32_e32 v207, v207, v137
	v_exp_f32_e32 v200, v200
	v_exp_f32_e32 v201, v201
	v_exp_f32_e32 v202, v202
	v_exp_f32_e32 v203, v203
	v_exp_f32_e32 v204, v204
	v_exp_f32_e32 v205, v205
	v_exp_f32_e32 v206, v206
	v_exp_f32_e32 v207, v207
	v_cvt_pk_bf16_f32 v246, v200, v201
	v_cvt_pk_bf16_f32 v247, v202, v203
	v_cvt_pk_bf16_f32 v248, v204, v205
	v_cvt_pk_bf16_f32 v249, v206, v207
	v_add_f32_e32 v14, v200, v201
	v_add_f32_e32 v15, v202, v203
	v_add_f32_e32 v0, v204, v205
	v_add_f32_e32 v245, v206, v207
	v_add_f32_e32 v14, v14, v15
	v_add_f32_e32 v0, v0, v245
	v_add_f32_e32 v14, v14, v0
	v_add_f32_e32 v244, v244, v14
	s_waitcnt lgkmcnt(0)
	v_mfma_f32_32x32x16_bf16 v[32:47], v[232:235], v[246:249], v[32:47]
	v_mfma_f32_32x32x16_bf16 v[16:31], v[236:239], v[246:249], v[16:31]
	v_add_f32_e32 v136, v136, v244
	s_branch .LBB0_394
; __device__ __forceinline__ void attn_item(const int WV, const Params& P, int bh, int qb) {
;     ...
;     if (kt * 64 <= q0 + 31) {
;       const float* cks = (const float*)(cur + 128 * KP);
;       f32x16 st[2];
; #pragma unroll
;       for (int kb = 0; kb < 2; ++kb) {
; #pragma unroll
;         for (int gq = 0; gq < 4; ++gq) {
;           f32x4 ck4 = *(const f32x4*)(cks + kb * 32 + gq * 8 + hf * 4);
;           st[kb][gq * 4 + 0] = ck4[0]; st[kb][gq * 4 + 1] = ck4[1]; st[kb][gq * 4 + 2] = ck4[2]; st[kb][gq * 4 + 3] = ck4[3];
;         }
; #pragma unroll
;         for (int s = 0; s < 4; ++s) {
;           bf16x8 a = *(const bf16x8*)(cur + (kb * 32 + n) * KP + s * 32 + hf * 16);
;           st[kb] = __builtin_amdgcn_mfma_f32_32x32x16_bf16(a, qf[s], st[kb], 0, 0, 0);
;         }
;       }
;       if (kt * 64 + 63 > q0) {
; #pragma unroll
;         for (int kb = 0; kb < 2; ++kb)
; #pragma unroll
;           for (int i = 0; i < 16; ++i) {
;             int key = kt * 64 + kb * 32 + (i >> 2) * 8 + hf * 4 + (i & 3);
;             if (key > q0 + n) st[kb][i] = -INFINITY;
;           }
;       }
.Lat2_slow:
	v_cmp_le_i32_e32 vcc, s28, v129
	s_and_saveexec_b64 s[12:13], vcc
	s_cbranch_execz .LBB0_390
	s_and_b32 s34, s33, 2
	s_mulk_i32 s34, 0x4900
	v_lshl_or_b32 v0, v113, 2, s34
	v_or_b32_e32 v2, s34, v118
	ds_read_b128 v[64:67], v0 offset:18432
	ds_read_b128 v[68:71], v0 offset:18464
	ds_read_b128 v[72:75], v0 offset:18496
	ds_read_b128 v[76:79], v0 offset:18528
	v_add_u32_e32 v10, v2, v134
	ds_read_b128 v[200:203], v10
	ds_read_b128 v[204:207], v10 offset:32
	ds_read_b128 v[208:211], v10 offset:64
	ds_read_b128 v[212:215], v10 offset:96
	ds_read_b128 v[48:51], v0 offset:18560
	ds_read_b128 v[52:55], v0 offset:18592
	ds_read_b128 v[56:59], v0 offset:18624
	ds_read_b128 v[60:63], v0 offset:18656
	ds_read_b128 v[216:219], v10 offset:4608
	ds_read_b128 v[220:223], v10 offset:4640
	ds_read_b128 v[224:227], v10 offset:4672
	s_add_i32 s20, s28, 63
	v_cmp_gt_i32_e32 vcc, s20, v116
	s_waitcnt lgkmcnt(10)
	v_mfma_f32_32x32x16_bf16 v[64:79], v[200:203], v[80:83], v[64:79]
	ds_read_b128 v[228:231], v10 offset:4704
	s_waitcnt lgkmcnt(10)
	v_mfma_f32_32x32x16_bf16 v[64:79], v[204:207], v[84:87], v[64:79]
	s_waitcnt lgkmcnt(9)
	v_mfma_f32_32x32x16_bf16 v[64:79], v[208:211], v[88:91], v[64:79]
	s_waitcnt lgkmcnt(8)
	v_mfma_f32_32x32x16_bf16 v[64:79], v[212:215], v[92:95], v[64:79]
	s_waitcnt lgkmcnt(3)
	v_mfma_f32_32x32x16_bf16 v[48:63], v[216:219], v[80:83], v[48:63]
	s_waitcnt lgkmcnt(2)
	v_mfma_f32_32x32x16_bf16 v[48:63], v[220:223], v[84:87], v[48:63]
	s_waitcnt lgkmcnt(1)
	v_mfma_f32_32x32x16_bf16 v[48:63], v[224:227], v[88:91], v[48:63]
	s_waitcnt lgkmcnt(0)
	v_mfma_f32_32x32x16_bf16 v[48:63], v[228:231], v[92:95], v[48:63]
	s_nop 1
	s_and_saveexec_b64 s[20:21], vcc
	s_cbranch_execz .LBB0_389
	v_add_u32_e32 v0, s28, v113
	v_cmp_lt_i32_e32 vcc, v0, v135
	v_add_u32_e32 v2, 2, v0
	s_nop 0
	v_cndmask_b32_e32 v65, v171, v65, vcc
	v_cmp_le_i32_e32 vcc, v0, v135
	s_nop 1
	v_cndmask_b32_e32 v64, v171, v64, vcc
	v_cmp_le_i32_e32 vcc, v2, v135
	v_add_u32_e32 v2, 3, v0
	s_nop 0
	v_cndmask_b32_e32 v66, v171, v66, vcc
	v_cmp_le_i32_e32 vcc, v2, v135
	v_add_u32_e32 v2, 8, v0
	s_nop 0
	v_cndmask_b32_e32 v67, v171, v67, vcc
	v_cmp_le_i32_e32 vcc, v2, v135
	v_add_u32_e32 v2, 9, v0
	s_nop 0
	v_cndmask_b32_e32 v68, v171, v68, vcc
	v_cmp_le_i32_e32 vcc, v2, v135
	v_add_u32_e32 v2, 10, v0
	s_nop 0
	v_cndmask_b32_e32 v69, v171, v69, vcc
	v_cmp_le_i32_e32 vcc, v2, v135
	v_add_u32_e32 v2, 11, v0
	s_nop 0
	v_cndmask_b32_e32 v70, v171, v70, vcc
	v_cmp_le_i32_e32 vcc, v2, v135
	v_add_u32_e32 v2, 16, v0
	s_nop 0
	v_cndmask_b32_e32 v71, v171, v71, vcc
	v_cmp_le_i32_e32 vcc, v2, v135
	v_add_u32_e32 v2, 17, v0
	s_nop 0
	v_cndmask_b32_e32 v72, v171, v72, vcc
	v_cmp_le_i32_e32 vcc, v2, v135
	v_add_u32_e32 v2, 18, v0
	s_nop 0
	v_cndmask_b32_e32 v73, v171, v73, vcc
	v_cmp_le_i32_e32 vcc, v2, v135
	v_add_u32_e32 v2, 19, v0
	s_nop 0
	v_cndmask_b32_e32 v74, v171, v74, vcc
	v_cmp_le_i32_e32 vcc, v2, v135
	v_add_u32_e32 v2, 24, v0
	s_nop 0
	v_cndmask_b32_e32 v75, v171, v75, vcc
	v_cmp_le_i32_e32 vcc, v2, v135
	v_add_u32_e32 v2, 25, v0
	s_nop 0
	v_cndmask_b32_e32 v76, v171, v76, vcc
	v_cmp_le_i32_e32 vcc, v2, v135
	v_add_u32_e32 v2, 26, v0
	s_nop 0
	v_cndmask_b32_e32 v77, v171, v77, vcc
	v_cmp_le_i32_e32 vcc, v2, v135
	v_add_u32_e32 v2, 27, v0
	s_nop 0
	v_cndmask_b32_e32 v78, v171, v78, vcc
	v_cmp_le_i32_e32 vcc, v2, v135
	v_add_u32_e32 v2, 32, v0
	s_nop 0
	v_cndmask_b32_e32 v79, v171, v79, vcc
	v_cmp_le_i32_e32 vcc, v2, v135
	v_add_u32_e32 v2, 33, v0
	s_nop 0
	v_cndmask_b32_e32 v48, v171, v48, vcc
	v_cmp_le_i32_e32 vcc, v2, v135
	v_add_u32_e32 v2, 34, v0
	s_nop 0
	v_cndmask_b32_e32 v49, v171, v49, vcc
	v_cmp_le_i32_e32 vcc, v2, v135
	v_add_u32_e32 v2, 35, v0
	s_nop 0
	v_cndmask_b32_e32 v50, v171, v50, vcc
	v_cmp_le_i32_e32 vcc, v2, v135
	v_add_u32_e32 v2, 40, v0
	s_nop 0
	v_cndmask_b32_e32 v51, v171, v51, vcc
	v_cmp_le_i32_e32 vcc, v2, v135
	v_add_u32_e32 v2, 41, v0
	s_nop 0
	v_cndmask_b32_e32 v52, v171, v52, vcc
	v_cmp_le_i32_e32 vcc, v2, v135
	v_add_u32_e32 v2, 42, v0
	s_nop 0
	v_cndmask_b32_e32 v53, v171, v53, vcc
	v_cmp_le_i32_e32 vcc, v2, v135
	v_add_u32_e32 v2, 43, v0
	s_nop 0
	v_cndmask_b32_e32 v54, v171, v54, vcc
	v_cmp_le_i32_e32 vcc, v2, v135
	v_add_u32_e32 v2, 48, v0
	s_nop 0
	v_cndmask_b32_e32 v55, v171, v55, vcc
	v_cmp_le_i32_e32 vcc, v2, v135
	v_add_u32_e32 v2, 49, v0
	s_nop 0
	v_cndmask_b32_e32 v56, v171, v56, vcc
	v_cmp_le_i32_e32 vcc, v2, v135
	v_add_u32_e32 v2, 50, v0
	s_nop 0
	v_cndmask_b32_e32 v57, v171, v57, vcc
	v_cmp_le_i32_e32 vcc, v2, v135
	v_add_u32_e32 v2, 51, v0
	s_nop 0
	v_cndmask_b32_e32 v58, v171, v58, vcc
	v_cmp_le_i32_e32 vcc, v2, v135
	v_add_u32_e32 v2, 56, v0
	s_nop 0
	v_cndmask_b32_e32 v59, v171, v59, vcc
	v_cmp_le_i32_e32 vcc, v2, v135
	v_add_u32_e32 v2, 57, v0
	s_nop 0
	v_cndmask_b32_e32 v60, v171, v60, vcc
	v_cmp_le_i32_e32 vcc, v2, v135
	v_add_u32_e32 v2, 58, v0
	v_add_u32_e32 v0, 59, v0
	v_cndmask_b32_e32 v61, v171, v61, vcc
	v_cmp_le_i32_e32 vcc, v2, v135
	s_nop 1
	v_cndmask_b32_e32 v62, v171, v62, vcc
	v_cmp_le_i32_e32 vcc, v0, v135
	s_nop 1
	v_cndmask_b32_e32 v63, v171, v63, vcc
